# XCC-local seam barriers: wave 1 issues the L1 invalidate in parallel with thread 0's arrival/poll protocol; stacked
# baseline (speedup 1.0000x reference)
; __device__ __forceinline__ unsigned xb_ld(unsigned* p)              { return __hip_atomic_load(p, __ATOMIC_RELAXED, __HIP_MEMORY_SCOPE_AGENT); }
; __device__ __forceinline__ unsigned xb_add(unsigned* p, unsigned v) { return __hip_atomic_fetch_add(p, v, __ATOMIC_RELAXED, __HIP_MEMORY_SCOPE_AGENT); }
; #define XB_SPIN(cond, bar) do { unsigned _sp = 0; while (cond) { __builtin_amdgcn_s_sleep(1); \
;     if ((++_sp & 255u) == 0u) { if (xb_ld(&(bar)[XB_TMO])) break; if (_sp > XB_SPIN_CAP) { atomicAdd(&(bar)[XB_TMO], 1u); break; } } } } while (0)
; #define x (arg_in(0))
; __device__ __forceinline__ void xcd_local_barrier(const XcdBarrier& b) {
;     asm volatile("s_waitcnt vmcnt(0)" ::: "memory");
;     __syncthreads();
;     if (threadIdx.x == 0) {
;         unsigned* bar = b.bar;
;         __builtin_amdgcn_s_waitcnt(0);
;         unsigned nloc = b.st[0], nx = b.st[1];
;         if (nloc == 0u) { xcd_barrier_complete(bar, b.x, nloc, nx); b.st[0] = nloc; b.st[1] = nx; }
;         const unsigned old = xb_add(&bar[XB_XSUB2(b.x)], 1u);
;         const unsigned gen = old / nloc;
;         if (old + 1u == (gen + 1u) * nloc) xb_add(&bar[XB_XGEN2(b.x)], 1u);
;         else XB_SPIN(xb_ld(&bar[XB_XGEN2(b.x)]) == gen, bar);
;         __builtin_amdgcn_fence(__ATOMIC_ACQUIRE, "agent");
;         asm volatile("s_waitcnt vmcnt(0)" ::: "memory");
.LBB0_118:
	s_and_b64 vcc, exec, s[36:37]
	s_cbranch_vccz .LBB0_153
	s_waitcnt vmcnt(0)
	s_barrier
	v_readfirstlane_b32 s8, v212
	s_nop 0
	s_lshr_b32 s8, s8, 6
	s_cmp_lg_u32 s8, 1
	s_cbranch_scc1 .Lseam_noinv_7
	buffer_inv sc1
	s_waitcnt vmcnt(0)
.Lseam_noinv_7:
	s_mov_b64 s[40:41], exec
	v_readlane_b32 s14, v253, 0
	v_readlane_b32 s15, v253, 1
	s_and_b64 s[14:15], s[40:41], s[14:15]
	s_mov_b64 exec, s[14:15]
	s_cbranch_execz .LBB0_152
	v_readlane_b32 s8, v254, 36
	s_waitcnt vmcnt(0) expcnt(0) lgkmcnt(0)
	s_nop 0
	v_mov_b32_e32 v0, s8
	ds_read_b32 v0, v0
	v_readlane_b32 s8, v254, 37
	s_waitcnt lgkmcnt(0)
	v_cmp_ne_u32_e32 vcc, 0, v0
	v_mov_b32_e32 v1, s8
	ds_read_b32 v1, v1
	s_cbranch_vccnz .LBB0_135
	s_mov_b32 s14, 1
	s_branch .LBB0_123

; __device__ __forceinline__ unsigned xb_ld(unsigned* p)              { return __hip_atomic_load(p, __ATOMIC_RELAXED, __HIP_MEMORY_SCOPE_AGENT); }
; __device__ __forceinline__ unsigned xb_add(unsigned* p, unsigned v) { return __hip_atomic_fetch_add(p, v, __ATOMIC_RELAXED, __HIP_MEMORY_SCOPE_AGENT); }
; #define XB_SPIN(cond, bar) do { unsigned _sp = 0; while (cond) { __builtin_amdgcn_s_sleep(1); \
;     if ((++_sp & 255u) == 0u) { if (xb_ld(&(bar)[XB_TMO])) break; if (_sp > XB_SPIN_CAP) { atomicAdd(&(bar)[XB_TMO], 1u); break; } } } } while (0)
; #define x (arg_in(0))
; __device__ __forceinline__ void xcd_local_barrier(const XcdBarrier& b) {
;     asm volatile("s_waitcnt vmcnt(0)" ::: "memory");
;     __syncthreads();
;     if (threadIdx.x == 0) {
;         unsigned* bar = b.bar;
;         __builtin_amdgcn_s_waitcnt(0);
;         unsigned nloc = b.st[0], nx = b.st[1];
;         if (nloc == 0u) { xcd_barrier_complete(bar, b.x, nloc, nx); b.st[0] = nloc; b.st[1] = nx; }
;         const unsigned old = xb_add(&bar[XB_XSUB2(b.x)], 1u);
;         const unsigned gen = old / nloc;
;         if (old + 1u == (gen + 1u) * nloc) xb_add(&bar[XB_XGEN2(b.x)], 1u);
;         else XB_SPIN(xb_ld(&bar[XB_XGEN2(b.x)]) == gen, bar);
;         __builtin_amdgcn_fence(__ATOMIC_ACQUIRE, "agent");
;         asm volatile("s_waitcnt vmcnt(0)" ::: "memory");
.LBB0_248:
	s_and_b64 vcc, exec, s[36:37]
	s_cbranch_vccz .LBB0_283
	s_waitcnt vmcnt(0)
	s_waitcnt vmcnt(0)
	s_barrier
	v_readfirstlane_b32 s8, v212
	s_nop 0
	s_lshr_b32 s8, s8, 6
	s_cmp_lg_u32 s8, 1
	s_cbranch_scc1 .Lseam_noinv_6
	buffer_inv sc1
	s_waitcnt vmcnt(0)

; __device__ __forceinline__ unsigned xb_ld(unsigned* p)              { return __hip_atomic_load(p, __ATOMIC_RELAXED, __HIP_MEMORY_SCOPE_AGENT); }
; __device__ __forceinline__ unsigned xb_add(unsigned* p, unsigned v) { return __hip_atomic_fetch_add(p, v, __ATOMIC_RELAXED, __HIP_MEMORY_SCOPE_AGENT); }
; #define XB_SPIN(cond, bar) do { unsigned _sp = 0; while (cond) { __builtin_amdgcn_s_sleep(1); \
;     if ((++_sp & 255u) == 0u) { if (xb_ld(&(bar)[XB_TMO])) break; if (_sp > XB_SPIN_CAP) { atomicAdd(&(bar)[XB_TMO], 1u); break; } } } } while (0)
; #define x (arg_in(0))
; __device__ __forceinline__ void xcd_local_barrier(const XcdBarrier& b) {
;     asm volatile("s_waitcnt vmcnt(0)" ::: "memory");
;     __syncthreads();
;     if (threadIdx.x == 0) {
;         unsigned* bar = b.bar;
;         __builtin_amdgcn_s_waitcnt(0);
;         unsigned nloc = b.st[0], nx = b.st[1];
;         if (nloc == 0u) { xcd_barrier_complete(bar, b.x, nloc, nx); b.st[0] = nloc; b.st[1] = nx; }
;         const unsigned old = xb_add(&bar[XB_XSUB2(b.x)], 1u);
;         const unsigned gen = old / nloc;
;         if (old + 1u == (gen + 1u) * nloc) xb_add(&bar[XB_XGEN2(b.x)], 1u);
;         else XB_SPIN(xb_ld(&bar[XB_XGEN2(b.x)]) == gen, bar);
;         __builtin_amdgcn_fence(__ATOMIC_ACQUIRE, "agent");
;         asm volatile("s_waitcnt vmcnt(0)" ::: "memory");
.LBB0_1071:
	s_waitcnt vmcnt(0)
	s_waitcnt vmcnt(0)
	s_barrier
	v_readfirstlane_b32 s8, v212
	s_nop 0
	s_lshr_b32 s8, s8, 6
	s_cmp_lg_u32 s8, 1
	s_cbranch_scc1 .Lseam_noinv_1
	buffer_inv sc1
	s_waitcnt vmcnt(0)
.Lseam_noinv_1:
	s_mov_b64 s[38:39], exec
	v_readlane_b32 s12, v253, 0
	v_readlane_b32 s13, v253, 1
	s_and_b64 s[12:13], s[38:39], s[12:13]
	s_mov_b64 exec, s[12:13]
	s_cbranch_execnz .LBB0_1072
	s_getpc_b64 s[98:99]
